# added: attention unit index low-6-bit permutation so an XCD's 8 workgroups take adjacent key blocks (K/V halo reuse in L2)
# baseline (speedup 1.0000x reference)
.LBB0_363:
	s_or_b64 exec, exec, s[0:1]
	v_mov_b32_e32 v6, v254
	s_waitcnt lgkmcnt(0)
	s_barrier
	v_writelane_b32 v255, s94, 18
	v_and_b32_e32 v0, 7, v6
	v_lshlrev_b32_e32 v0, 2, v0
	global_load_dword v135, v0, s[50:51]
	v_readfirstlane_b32 s35, v6
	s_ashr_i32 s34, s35, 6
	s_and_b32 s100, s2, 7
	s_lshl_b32 s100, s100, 3
	s_bfe_u32 s101, s2, 0x30003
	s_or_b32 s100, s100, s101
	s_andn2_b32 s101, s2, 63
	s_or_b32 s100, s100, s101
	s_cmpk_gt_i32 s2, 0x5ff
	v_writelane_b32 v255, s95, 19
	s_cselect_b64 s[0:1], -1, 0
	v_writelane_b32 v255, s0, 20
	s_and_b64 vcc, exec, s[0:1]
	s_nop 0
	v_writelane_b32 v255, s1, 21
	s_cbranch_vccz .LBB0_366
	s_add_i32 s0, s100, 0xfffffa00
	s_lshr_b32 s6, s0, 9
	s_bfe_u32 s0, s100, 0x10008
	s_lshl_b32 s1, s100, 6
	s_and_b32 s97, s1, 0x3fc0
	s_lshl_b32 s1, s0, 6
	s_or_b32 s8, s1, 0x200
	s_or_b32 s10, s1, 0x280
	s_lshl_b32 s0, s0, 2
	s_ashr_i32 s1, s35, 7
	s_add_i32 s89, s1, s0
	s_lshl_b32 s0, s34, 5
	s_and_b32 s0, s0, 32
	s_lshl_b32 s4, s89, 6
	s_or_b32 s13, s0, s97
	s_mov_b32 s1, 1
	s_cbranch_execz .LBB0_367
	s_mov_b32 s0, -1
	s_movk_i32 s68, 0x200
	s_movk_i32 s69, 0x7f
	s_movk_i32 s66, 0xc0
	s_mov_b32 s67, 0
	s_mov_b32 s12, s4
	s_mov_b32 s78, 1
	s_branch .LBB0_368

.LBB0_367:
	s_ashr_i32 s1, s100, 6
	s_mul_hi_i32 s4, s1, 0x2aaaaaab
	s_lshr_b32 s5, s4, 31
	s_ashr_i32 s4, s4, 1
	s_add_i32 s6, s4, s5
	s_mul_i32 s4, s6, 12
	s_sub_i32 s5, s1, s4
	s_ashr_i32 s4, s5, 2
	s_lshl_b32 s8, s4, 1
	s_lshr_b32 s9, 64, s8
	s_and_b32 s0, s100, 63
	s_and_b32 s7, s1, 3
	s_lshl_b32 s1, 1, s8
	s_sub_i32 s8, 6, s8
	s_add_i32 s9, s9, -1
	s_lshr_b32 s67, s0, s8
	s_and_b32 s0, s9, s0
	s_lshl_b32 s97, s0, 8
	s_lshl_b32 s0, s4, 8
	s_lshl_b32 s4, s7, 6
	s_or_b32 s12, s0, s4
	s_lshl_b32 s0, s34, 5
	s_add_i32 s13, s0, s97
	s_and_b32 s0, s5, -4
	s_or_b32 s0, s0, s7
	s_add_i32 s8, s12, 0x600
	s_add_i32 s10, s12, 0x900
	s_movk_i32 s68, 0x300
	s_add_i32 s4, s12, 0x300
	s_add_i32 s89, s0, 8
	s_mov_b32 s78, 0
	s_movk_i32 s69, 0x80
	s_movk_i32 s66, 0x180

.LBB0_393:
	s_or_b64 exec, exec, s[8:9]
	s_add_i32 s86, s86, s38
	s_waitcnt lgkmcnt(0)
	s_barrier
	s_cmpk_gt_i32 s86, 0x9ff
	s_cselect_b64 s[74:75], -1, 0
	v_mov_b64_e32 v[118:119], v[50:51]
	v_mov_b64_e32 v[122:123], v[54:55]
	v_mov_b64_e32 v[126:127], v[58:59]
	v_mov_b64_e32 v[130:131], v[62:63]
	s_and_b64 vcc, exec, s[74:75]
	s_mov_b32 s76, s6
	s_mov_b32 s90, s1
	s_mov_b32 s91, s67
	s_mov_b32 s87, s97
	s_mov_b32 s88, s13
	s_mov_b32 s80, s89
	s_mov_b32 s94, s69
	s_mov_b32 s92, s68
	s_mov_b32 s95, s12
	s_mov_b32 s93, s0
	s_mov_b32 s96, s78
	v_mov_b64_e32 v[116:117], v[48:49]
	v_mov_b64_e32 v[120:121], v[52:53]
	v_mov_b64_e32 v[124:125], v[56:57]
	v_mov_b64_e32 v[128:129], v[60:61]
	s_cbranch_vccnz .LBB0_417
	s_and_b32 s100, s86, 7
	s_lshl_b32 s100, s100, 3
	s_bfe_u32 s101, s86, 0x30003
	s_or_b32 s100, s100, s101
	s_andn2_b32 s101, s86, 63
	s_or_b32 s100, s100, s101
	s_cmpk_gt_i32 s86, 0x5ff
	s_mov_b64 s[46:47], -1
	s_cbranch_scc0 .LBB0_396
	s_add_i32 s7, s100, 0xfffffa00
	s_lshr_b32 s76, s7, 9
	s_bfe_u32 s7, s100, 0x10008
	s_lshl_b32 s8, s100, 6
	s_and_b32 s87, s8, 0x3fc0
	s_lshl_b32 s8, s7, 6
	s_or_b32 s14, s8, 0x200
	s_or_b32 s10, s8, 0x280
	s_lshl_b32 s7, s7, 2
	v_readlane_b32 s8, v255, 24
	s_add_i32 s80, s7, s8
	s_lshl_b32 s8, s80, 6
	s_or_b32 s88, s87, s82
	s_mov_b64 s[46:47], 0
.LBB0_396:
	s_andn2_b64 vcc, exec, s[46:47]
	s_mov_b32 s90, 1
	s_cbranch_vccnz .LBB0_403
	s_ashr_i32 s8, s100, 6
	s_mul_hi_i32 s9, s8, 0x2aaaaaab
	s_lshr_b32 s10, s9, 31
	s_ashr_i32 s9, s9, 1
	s_add_i32 s76, s9, s10
	s_mul_i32 s9, s76, 12
	s_sub_i32 s9, s8, s9
	s_ashr_i32 s10, s9, 2
	s_and_b32 s11, s8, 3
	s_lshl_b32 s8, s10, 1
	s_lshr_b32 s14, 64, s8
	s_and_b32 s7, s100, 63
	s_lshl_b32 s90, 1, s8
	s_sub_i32 s8, 6, s8
	s_add_i32 s14, s14, -1
	s_lshr_b32 s91, s7, s8
	s_and_b32 s7, s14, s7
	s_lshl_b32 s87, s7, 8
	s_lshl_b32 s7, s10, 8
	s_lshl_b32 s8, s11, 6
	s_or_b32 s95, s7, s8
	s_and_b32 s7, s9, -4
	s_or_b32 s93, s7, s11
	s_add_i32 s14, s95, 0x600
	s_add_i32 s10, s95, 0x900
	s_movk_i32 s92, 0x300
	s_add_i32 s8, s95, 0x300
	s_add_i32 s88, s87, s81
	s_add_i32 s80, s93, 8
	s_mov_b32 s96, 0
	s_movk_i32 s94, 0x80
	s_movk_i32 s66, 0x180
	s_branch .LBB0_404

.LBB0_1223:
	s_or_b64 exec, exec, s[0:1]
	v_mov_b32_e32 v6, v254
	s_waitcnt lgkmcnt(0)
	s_barrier
	v_readlane_b32 s0, v255, 20
	v_and_b32_e32 v0, 7, v6
	v_lshlrev_b32_e32 v0, 2, v0
	global_load_dword v135, v0, s[50:51] offset:32
	v_readfirstlane_b32 s35, v6
	v_readlane_b32 s1, v255, 21
	s_ashr_i32 s34, s35, 6
	s_and_b32 s100, s2, 7
	s_lshl_b32 s100, s100, 3
	s_bfe_u32 s101, s2, 0x30003
	s_or_b32 s100, s100, s101
	s_andn2_b32 s101, s2, 63
	s_or_b32 s100, s100, s101
	s_and_b64 vcc, exec, s[0:1]
	s_cbranch_vccz .LBB0_1226
	s_add_i32 s0, s100, 0xfffffa00
	s_lshr_b32 s4, s0, 9
	s_bfe_u32 s0, s100, 0x10008
	s_lshl_b32 s1, s100, 6
	s_and_b32 s79, s1, 0x3fc0
	s_lshl_b32 s1, s0, 6
	s_or_b32 s10, s1, 0x200
	s_or_b32 s12, s1, 0x280
	s_lshl_b32 s0, s0, 2
	s_ashr_i32 s1, s35, 7
	s_add_i32 s81, s1, s0
	s_lshl_b32 s0, s34, 5
	s_and_b32 s0, s0, 32
	s_lshl_b32 s8, s81, 6
	s_or_b32 s7, s0, s79
	s_mov_b32 s1, 1
	s_cbranch_execz .LBB0_1227
	s_mov_b32 s0, -1
	s_movk_i32 s66, 0x200
	s_movk_i32 s67, 0x7f
	s_movk_i32 s64, 0xc0
	s_mov_b32 s65, 0
	s_mov_b32 s6, s8
	s_mov_b32 s74, 1
	s_branch .LBB0_1228

.LBB0_1227:
	s_ashr_i32 s1, s100, 6
	s_mul_hi_i32 s4, s1, 0x2aaaaaab
	s_lshr_b32 s5, s4, 31
	s_ashr_i32 s4, s4, 1
	s_add_i32 s4, s4, s5
	s_mul_i32 s5, s4, 12
	s_sub_i32 s5, s1, s5
	s_ashr_i32 s6, s5, 2
	s_lshl_b32 s7, s6, 1
	s_lshr_b32 s8, 64, s7
	s_and_b32 s0, s100, 63
	s_and_b32 s9, s1, 3
	s_lshl_b32 s1, 1, s7
	s_sub_i32 s7, 6, s7
	s_add_i32 s8, s8, -1
	s_lshr_b32 s65, s0, s7
	s_and_b32 s0, s8, s0
	s_lshl_b32 s79, s0, 8
	s_lshl_b32 s0, s6, 8
	s_lshl_b32 s6, s9, 6
	s_or_b32 s6, s0, s6
	s_lshl_b32 s0, s34, 5
	s_add_i32 s7, s0, s79
	s_and_b32 s0, s5, -4
	s_or_b32 s0, s0, s9
	s_add_i32 s10, s6, 0x600
	s_add_i32 s12, s6, 0x900
	s_movk_i32 s66, 0x300
	s_add_i32 s8, s6, 0x300
	s_add_i32 s81, s0, 8
	s_mov_b32 s74, 0
	s_movk_i32 s67, 0x80
	s_movk_i32 s64, 0x180

.LBB0_1253:
	s_or_b64 exec, exec, s[10:11]
	s_add_i32 s78, s78, s38
	s_waitcnt lgkmcnt(0)
	s_barrier
	s_cmpk_gt_i32 s78, 0x9ff
	s_cselect_b64 s[96:97], -1, 0
	v_mov_b64_e32 v[118:119], v[50:51]
	v_mov_b64_e32 v[122:123], v[54:55]
	v_mov_b64_e32 v[126:127], v[58:59]
	v_mov_b64_e32 v[130:131], v[62:63]
	s_and_b64 vcc, exec, s[96:97]
	s_mov_b32 s40, s4
	s_mov_b32 s84, s1
	s_mov_b32 s85, s65
	s_mov_b32 s70, s79
	s_mov_b32 s80, s7
	s_mov_b32 s69, s81
	s_mov_b32 s90, s67
	s_mov_b32 s86, s66
	s_mov_b32 s91, s6
	s_mov_b32 s87, s0
	s_mov_b32 s68, s74
	v_mov_b64_e32 v[116:117], v[48:49]
	v_mov_b64_e32 v[120:121], v[52:53]
	v_mov_b64_e32 v[124:125], v[56:57]
	v_mov_b64_e32 v[128:129], v[60:61]
	s_cbranch_vccnz .LBB0_1277
	s_and_b32 s100, s78, 7
	s_lshl_b32 s100, s100, 3
	s_bfe_u32 s101, s78, 0x30003
	s_or_b32 s100, s100, s101
	s_andn2_b32 s101, s78, 63
	s_or_b32 s100, s100, s101
	s_cmpk_gt_i32 s78, 0x5ff
	s_mov_b64 s[46:47], -1
	s_cbranch_scc0 .LBB0_1256
	s_add_i32 s5, s100, 0xfffffa00
	s_lshr_b32 s40, s5, 9
	s_bfe_u32 s5, s100, 0x10008
	s_lshl_b32 s10, s100, 6
	s_and_b32 s70, s10, 0x3fc0
	s_lshl_b32 s10, s5, 6
	s_or_b32 s14, s10, 0x200
	s_or_b32 s12, s10, 0x280
	s_lshl_b32 s5, s5, 2
	v_readlane_b32 s10, v255, 50
	s_add_i32 s69, s5, s10
	v_readlane_b32 s5, v255, 53
	s_lshl_b32 s10, s69, 6
	s_or_b32 s80, s70, s5
	s_mov_b64 s[46:47], 0
.LBB0_1256:
	s_andn2_b64 vcc, exec, s[46:47]
	s_mov_b32 s84, 1
	s_cbranch_vccnz .LBB0_1263
	s_ashr_i32 s10, s100, 6
	s_mul_hi_i32 s11, s10, 0x2aaaaaab
	s_lshr_b32 s12, s11, 31
	s_ashr_i32 s11, s11, 1
	s_add_i32 s40, s11, s12
	s_mul_i32 s11, s40, 12
	s_sub_i32 s11, s10, s11
	s_ashr_i32 s12, s11, 2
	s_and_b32 s13, s10, 3
	s_lshl_b32 s10, s12, 1
	s_lshr_b32 s14, 64, s10
	s_and_b32 s5, s100, 63
	s_lshl_b32 s84, 1, s10
	s_sub_i32 s10, 6, s10
	s_add_i32 s14, s14, -1
	s_lshr_b32 s85, s5, s10
	s_and_b32 s5, s14, s5
	s_lshl_b32 s70, s5, 8
	s_lshl_b32 s5, s12, 8
	s_lshl_b32 s10, s13, 6
	s_or_b32 s91, s5, s10
	v_readlane_b32 s5, v255, 52
	s_add_i32 s80, s70, s5
	s_and_b32 s5, s11, -4
	s_or_b32 s87, s5, s13
	s_add_i32 s14, s91, 0x600
	s_add_i32 s12, s91, 0x900
	s_movk_i32 s86, 0x300
	s_add_i32 s10, s91, 0x300
	s_add_i32 s69, s87, 8
	s_mov_b32 s68, 0
	s_movk_i32 s90, 0x80
	s_movk_i32 s64, 0x180
	s_branch .LBB0_1264

.LBB0_2083:
	s_or_b64 exec, exec, s[0:1]
	v_mov_b32_e32 v6, v254
	s_waitcnt lgkmcnt(0)
	s_barrier
	v_readlane_b32 s0, v255, 20
	v_and_b32_e32 v0, 7, v6
	v_lshlrev_b32_e32 v0, 2, v0
	global_load_dword v135, v0, s[50:51] offset:64
	v_readfirstlane_b32 s35, v6
	v_readlane_b32 s1, v255, 21
	s_ashr_i32 s34, s35, 6
	s_and_b32 s100, s2, 7
	s_lshl_b32 s100, s100, 3
	s_bfe_u32 s101, s2, 0x30003
	s_or_b32 s100, s100, s101
	s_andn2_b32 s101, s2, 63
	s_or_b32 s100, s100, s101
	s_and_b64 vcc, exec, s[0:1]
	s_cbranch_vccz .LBB0_2086
	s_add_i32 s0, s100, 0xfffffa00
	s_lshr_b32 s4, s0, 9
	s_bfe_u32 s0, s100, 0x10008
	s_lshl_b32 s1, s100, 6
	s_and_b32 s93, s1, 0x3fc0
	s_lshl_b32 s1, s0, 6
	s_or_b32 s8, s1, 0x200
	s_or_b32 s12, s1, 0x280
	s_lshl_b32 s0, s0, 2
	s_ashr_i32 s1, s35, 7
	s_add_i32 s81, s1, s0
	s_lshl_b32 s0, s34, 5
	s_and_b32 s0, s0, 32
	s_lshl_b32 s10, s81, 6
	s_or_b32 s7, s0, s93
	s_mov_b32 s1, 1
	s_cbranch_execz .LBB0_2087
	s_mov_b32 s0, -1
	s_movk_i32 s66, 0x200
	s_movk_i32 s67, 0x7f
	s_movk_i32 s64, 0xc0
	s_mov_b32 s65, 0
	s_mov_b32 s6, s10
	s_mov_b32 s92, 1
	s_branch .LBB0_2088

.LBB0_2087:
	s_ashr_i32 s1, s100, 6
	s_mul_hi_i32 s4, s1, 0x2aaaaaab
	s_lshr_b32 s5, s4, 31
	s_ashr_i32 s4, s4, 1
	s_add_i32 s4, s4, s5
	s_mul_i32 s5, s4, 12
	s_sub_i32 s5, s1, s5
	s_ashr_i32 s6, s5, 2
	s_lshl_b32 s7, s6, 1
	s_lshr_b32 s8, 64, s7
	s_and_b32 s0, s100, 63
	s_and_b32 s9, s1, 3
	s_lshl_b32 s1, 1, s7
	s_sub_i32 s7, 6, s7
	s_add_i32 s8, s8, -1
	s_lshr_b32 s65, s0, s7
	s_and_b32 s0, s8, s0
	s_lshl_b32 s93, s0, 8
	s_lshl_b32 s0, s6, 8
	s_lshl_b32 s6, s9, 6
	s_or_b32 s6, s0, s6
	s_lshl_b32 s0, s34, 5
	s_add_i32 s7, s0, s93
	s_and_b32 s0, s5, -4
	s_or_b32 s0, s0, s9
	s_add_i32 s8, s6, 0x600
	s_add_i32 s12, s6, 0x900
	s_movk_i32 s66, 0x300
	s_add_i32 s10, s6, 0x300
	s_add_i32 s81, s0, 8
	s_mov_b32 s92, 0
	s_movk_i32 s67, 0x80
	s_movk_i32 s64, 0x180

.LBB0_2113:
	s_or_b64 exec, exec, s[12:13]
	s_add_i32 s78, s78, s38
	s_waitcnt lgkmcnt(0)
	s_barrier
	s_cmpk_gt_i32 s78, 0x9ff
	s_cselect_b64 s[40:41], -1, 0
	v_mov_b64_e32 v[118:119], v[50:51]
	v_mov_b64_e32 v[122:123], v[54:55]
	v_mov_b64_e32 v[126:127], v[58:59]
	v_mov_b64_e32 v[130:131], v[62:63]
	s_and_b64 vcc, exec, s[40:41]
	s_mov_b32 s74, s4
	s_mov_b32 s84, s1
	s_mov_b32 s85, s65
	s_mov_b32 s79, s93
	s_mov_b32 s80, s7
	s_mov_b32 s68, s81
	s_mov_b32 s90, s67
	s_mov_b32 s86, s66
	s_mov_b32 s91, s6
	s_mov_b32 s87, s0
	s_mov_b32 s70, s92
	v_mov_b64_e32 v[116:117], v[48:49]
	v_mov_b64_e32 v[120:121], v[52:53]
	v_mov_b64_e32 v[124:125], v[56:57]
	v_mov_b64_e32 v[128:129], v[60:61]
	s_cbranch_vccnz .LBB0_2137
	s_and_b32 s100, s78, 7
	s_lshl_b32 s100, s100, 3
	s_bfe_u32 s101, s78, 0x30003
	s_or_b32 s100, s100, s101
	s_andn2_b32 s101, s78, 63
	s_or_b32 s100, s100, s101
	s_cmpk_gt_i32 s78, 0x5ff
	s_mov_b64 s[46:47], -1
	s_cbranch_scc0 .LBB0_2116
	s_add_i32 s5, s100, 0xfffffa00
	s_lshr_b32 s74, s5, 9
	s_bfe_u32 s5, s100, 0x10008
	s_lshl_b32 s8, s100, 6
	s_lshl_b32 s12, s5, 6
	s_and_b32 s79, s8, 0x3fc0
	s_or_b32 s8, s12, 0x200
	s_or_b32 s14, s12, 0x280
	s_lshl_b32 s5, s5, 2
	v_readlane_b32 s12, v255, 52
	s_add_i32 s68, s5, s12
	v_readlane_b32 s5, v255, 53
	s_lshl_b32 s12, s68, 6
	s_or_b32 s80, s79, s5
	s_mov_b64 s[46:47], 0
.LBB0_2116:
	s_andn2_b64 vcc, exec, s[46:47]
	s_mov_b32 s84, 1
	s_cbranch_vccnz .LBB0_2123
	s_ashr_i32 s8, s100, 6
	s_mul_hi_i32 s12, s8, 0x2aaaaaab
	s_lshr_b32 s13, s12, 31
	s_ashr_i32 s12, s12, 1
	s_add_i32 s74, s12, s13
	s_mul_i32 s12, s74, 12
	s_sub_i32 s13, s8, s12
	s_ashr_i32 s12, s13, 2
	s_and_b32 s15, s8, 3
	s_lshl_b32 s8, s12, 1
	s_lshr_b32 s14, 64, s8
	s_and_b32 s5, s100, 63
	s_lshl_b32 s84, 1, s8
	s_sub_i32 s8, 6, s8
	s_add_i32 s14, s14, -1
	s_lshr_b32 s85, s5, s8
	s_and_b32 s5, s14, s5
	s_lshl_b32 s79, s5, 8
	s_lshl_b32 s5, s12, 8
	s_lshl_b32 s8, s15, 6
	s_or_b32 s91, s5, s8
	s_and_b32 s5, s13, -4
	s_or_b32 s87, s5, s15
	s_add_i32 s8, s91, 0x600
	s_add_i32 s14, s91, 0x900
	s_movk_i32 s86, 0x300
	s_add_i32 s12, s91, 0x300
	s_add_i32 s80, s79, s69
	s_add_i32 s68, s87, 8
	s_mov_b32 s70, 0
	s_movk_i32 s90, 0x80
	s_movk_i32 s64, 0x180
	s_branch .LBB0_2124

.LBB0_2947:
	s_or_b64 exec, exec, s[0:1]
	v_mov_b32_e32 v6, v254
	s_waitcnt lgkmcnt(0)
	s_barrier
	v_readlane_b32 s0, v255, 20
	v_and_b32_e32 v0, 7, v6
	v_lshlrev_b32_e32 v0, 2, v0
	global_load_dword v135, v0, s[50:51] offset:96
	v_readfirstlane_b32 s19, v6
	v_readlane_b32 s1, v255, 21
	s_ashr_i32 s18, s19, 6
	s_and_b32 s100, s2, 7
	s_lshl_b32 s100, s100, 3
	s_bfe_u32 s101, s2, 0x30003
	s_or_b32 s100, s100, s101
	s_andn2_b32 s101, s2, 63
	s_or_b32 s100, s100, s101
	s_and_b64 vcc, exec, s[0:1]
	s_cbranch_vccz .LBB0_2950
	s_add_i32 s0, s100, 0xfffffa00
	s_lshr_b32 s4, s0, 9
	s_bfe_u32 s0, s100, 0x10008
	s_lshl_b32 s1, s100, 6
	s_and_b32 s81, s1, 0x3fc0
	s_lshl_b32 s1, s0, 6
	s_or_b32 s6, s1, 0x200
	s_or_b32 s12, s1, 0x280
	s_lshl_b32 s0, s0, 2
	s_ashr_i32 s1, s19, 7
	s_add_i32 s82, s1, s0
	s_lshl_b32 s0, s18, 5
	s_and_b32 s0, s0, 32
	s_lshl_b32 s10, s82, 6
	s_or_b32 s9, s0, s81
	s_mov_b32 s1, 1
	s_cbranch_execz .LBB0_2951
	s_mov_b32 s0, -1
	s_movk_i32 s54, 0x200
	s_movk_i32 s55, 0x7f
	s_movk_i32 s52, 0xc0
	s_mov_b32 s53, 0
	s_mov_b32 s8, s10
	s_mov_b32 s83, 1
	s_branch .LBB0_2952

.LBB0_2951:
	s_ashr_i32 s1, s100, 6
	s_mul_hi_i32 s4, s1, 0x2aaaaaab
	s_lshr_b32 s5, s4, 31
	s_ashr_i32 s4, s4, 1
	s_add_i32 s4, s4, s5
	s_mul_i32 s5, s4, 12
	s_sub_i32 s5, s1, s5
	s_ashr_i32 s6, s5, 2
	s_lshl_b32 s8, s6, 1
	s_lshr_b32 s9, 64, s8
	s_and_b32 s0, s100, 63
	s_and_b32 s7, s1, 3
	s_lshl_b32 s1, 1, s8
	s_sub_i32 s8, 6, s8
	s_add_i32 s9, s9, -1
	s_lshr_b32 s53, s0, s8
	s_and_b32 s0, s9, s0
	s_lshl_b32 s81, s0, 8
	s_lshl_b32 s0, s6, 8
	s_lshl_b32 s6, s7, 6
	s_or_b32 s8, s0, s6
	s_lshl_b32 s0, s18, 5
	s_add_i32 s9, s0, s81
	s_and_b32 s0, s5, -4
	s_or_b32 s0, s0, s7
	s_add_i32 s6, s8, 0x600
	s_add_i32 s12, s8, 0x900
	s_movk_i32 s54, 0x300
	s_add_i32 s10, s8, 0x300
	s_add_i32 s82, s0, 8
	s_mov_b32 s83, 0
	s_movk_i32 s55, 0x80
	s_movk_i32 s52, 0x180

.LBB0_2977:
	s_or_b64 exec, exec, s[10:11]
	s_add_i32 s68, s68, s38
	s_waitcnt lgkmcnt(0)
	s_barrier
	s_cmpk_gt_i32 s68, 0x9ff
	s_cselect_b64 s[40:41], -1, 0
	v_mov_b64_e32 v[118:119], v[50:51]
	v_mov_b64_e32 v[122:123], v[54:55]
	v_mov_b64_e32 v[126:127], v[58:59]
	v_mov_b64_e32 v[130:131], v[62:63]
	s_and_b64 vcc, exec, s[40:41]
	s_mov_b32 s50, s4
	s_mov_b32 s72, s1
	s_mov_b32 s73, s53
	s_mov_b32 s69, s81
	s_mov_b32 s70, s9
	s_mov_b32 s71, s82
	s_mov_b32 s78, s55
	s_mov_b32 s74, s54
	s_mov_b32 s79, s8
	s_mov_b32 s75, s0
	s_mov_b32 s80, s83
	v_mov_b64_e32 v[116:117], v[48:49]
	v_mov_b64_e32 v[120:121], v[52:53]
	v_mov_b64_e32 v[124:125], v[56:57]
	v_mov_b64_e32 v[128:129], v[60:61]
	s_cbranch_vccnz .LBB0_3001
	s_and_b32 s100, s68, 7
	s_lshl_b32 s100, s100, 3
	s_bfe_u32 s101, s68, 0x30003
	s_or_b32 s100, s100, s101
	s_andn2_b32 s101, s68, 63
	s_or_b32 s100, s100, s101
	s_cmpk_gt_i32 s68, 0x5ff
	s_mov_b64 s[46:47], -1
	s_cbranch_scc0 .LBB0_2980
	s_add_i32 s5, s100, 0xfffffa00
	s_lshr_b32 s50, s5, 9
	s_bfe_u32 s5, s100, 0x10008
	s_lshl_b32 s10, s100, 6
	s_and_b32 s69, s10, 0x3fc0
	s_lshl_b32 s10, s5, 6
	s_lshl_b32 s5, s5, 2
	s_add_i32 s71, s5, s60
	s_or_b32 s16, s10, 0x200
	s_or_b32 s12, s10, 0x280
	s_lshl_b32 s10, s71, 6
	s_or_b32 s70, s69, s64
	s_mov_b64 s[46:47], 0
.LBB0_2980:
	s_andn2_b64 vcc, exec, s[46:47]
	s_mov_b32 s72, 1
	s_cbranch_vccnz .LBB0_2987
	s_ashr_i32 s10, s100, 6
	s_mul_hi_i32 s11, s10, 0x2aaaaaab
	s_lshr_b32 s12, s11, 31
	s_ashr_i32 s11, s11, 1
	s_add_i32 s50, s11, s12
	s_mul_i32 s11, s50, 12
	s_sub_i32 s11, s10, s11
	s_ashr_i32 s12, s11, 2
	s_and_b32 s13, s10, 3
	s_lshl_b32 s10, s12, 1
	s_lshr_b32 s16, 64, s10
	s_and_b32 s5, s100, 63
	s_lshl_b32 s72, 1, s10
	s_sub_i32 s10, 6, s10
	s_add_i32 s16, s16, -1
	s_lshr_b32 s73, s5, s10
	s_and_b32 s5, s16, s5
	s_lshl_b32 s69, s5, 8
	s_lshl_b32 s5, s12, 8
	s_lshl_b32 s10, s13, 6
	s_or_b32 s79, s5, s10
	s_and_b32 s5, s11, -4
	s_or_b32 s75, s5, s13
	s_add_i32 s16, s79, 0x600
	s_add_i32 s12, s79, 0x900
	s_movk_i32 s74, 0x300
	s_add_i32 s10, s79, 0x300
	s_add_i32 s70, s69, s61
	s_add_i32 s71, s75, 8
	s_mov_b32 s80, 0
	s_movk_i32 s78, 0x80
	s_movk_i32 s52, 0x180
	s_branch .LBB0_2988
